# v42 + AMX: attention steady loop row-max chain without the NaN-canonicalising v_max x,x,x ops (8 VALU fewer per two KV tiles)
# speedup vs baseline: 1.0041x; 1.0041x over previous
.LBB0_709:
	v_add_u32_e32 v202, s14, v237
	ds_read_b64_tr_b16 v[194:195], v202 offset:24576
	ds_read_b64_tr_b16 v[196:197], v202 offset:25088
	s_waitcnt lgkmcnt(9)
	v_mfma_f32_32x32x16_bf16 v[98:113], v[190:193], v[158:161], v[34:49]
	v_add_f32_e32 v82, v66, v67
	v_add_f32_e32 v82, v68, v82
	v_add_f32_e32 v82, v69, v82
	v_add_f32_e32 v82, v70, v82
	v_add_f32_e32 v82, v71, v82
	v_cvt_pk_bf16_f32 v150, v66, v67
	v_cvt_pk_bf16_f32 v151, v68, v69
	ds_read_b64_tr_b16 v[190:191], v202 offset:28672
	ds_read_b64_tr_b16 v[192:193], v202 offset:29184
	v_add_f32_e32 v66, v72, v82
	s_waitcnt lgkmcnt(10)
	v_mfma_f32_32x32x16_bf16 v[82:97], v[186:189], v[158:161], v[34:49]
	v_add_f32_e32 v66, v73, v66
	v_add_f32_e32 v66, v74, v66
	v_add_f32_e32 v130, v75, v66
	v_cvt_pk_bf16_f32 v152, v70, v71
	v_cvt_pk_bf16_f32 v153, v72, v73
	ds_read_b64_tr_b16 v[66:67], v202 offset:25600
	ds_read_b64_tr_b16 v[68:69], v202 offset:26112
	s_waitcnt lgkmcnt(11)
	v_mfma_f32_32x32x16_bf16 v[98:113], v[182:185], v[154:157], v[98:113]
	v_add_f32_e32 v70, v76, v130
	v_add_f32_e32 v70, v77, v70
	v_add_f32_e32 v70, v78, v70
	v_add_f32_e32 v130, v79, v70
	v_cvt_pk_bf16_f32 v142, v74, v75
	v_cvt_pk_bf16_f32 v143, v76, v77
	ds_read_b64_tr_b16 v[70:71], v202 offset:29696
	ds_read_b64_tr_b16 v[72:73], v202 offset:30208
	s_waitcnt lgkmcnt(12)
	v_mfma_f32_32x32x16_bf16 v[82:97], v[178:181], v[154:157], v[82:97]
	v_add_f32_e32 v74, v80, v130
	v_add_f32_e32 v74, v81, v74
	v_add_f32_e32 v74, v50, v74
	v_add_f32_e32 v130, v51, v74
	v_cvt_pk_bf16_f32 v144, v78, v79
	v_cvt_pk_bf16_f32 v145, v80, v81
	ds_read_b64_tr_b16 v[74:75], v202 offset:26624
	ds_read_b64_tr_b16 v[76:77], v202 offset:27136
	s_waitcnt lgkmcnt(13)
	v_mfma_f32_32x32x16_bf16 v[98:113], v[174:177], v[146:149], v[98:113]
	v_add_f32_e32 v78, v52, v130
	v_add_f32_e32 v78, v53, v78
	v_add_f32_e32 v78, v54, v78
	v_add_f32_e32 v78, v55, v78
	v_cvt_pk_bf16_f32 v134, v50, v51
	v_cvt_pk_bf16_f32 v135, v52, v53
	ds_read_b64_tr_b16 v[50:51], v202 offset:30720
	ds_read_b64_tr_b16 v[52:53], v202 offset:31232
	s_waitcnt lgkmcnt(14)
	v_mfma_f32_32x32x16_bf16 v[82:97], v[170:173], v[146:149], v[82:97]
	v_add_f32_e32 v78, v56, v78
	v_add_f32_e32 v78, v57, v78
	v_add_f32_e32 v78, v58, v78
	v_add_f32_e32 v78, v59, v78
	v_cvt_pk_bf16_f32 v136, v54, v55
	v_cvt_pk_bf16_f32 v137, v56, v57
	ds_read_b64_tr_b16 v[54:55], v202 offset:27648
	ds_read_b64_tr_b16 v[56:57], v202 offset:28160
	s_waitcnt lgkmcnt(14)
	v_mfma_f32_32x32x16_bf16 v[98:113], v[166:169], v[138:141], v[98:113]
	v_add_f32_e32 v78, v60, v78
	v_add_f32_e32 v78, v61, v78
	v_add_f32_e32 v78, v62, v78
	v_add_f32_e32 v78, v63, v78
	v_cvt_pk_bf16_f32 v130, v58, v59
	v_cvt_pk_bf16_f32 v131, v60, v61
	ds_read_b64_tr_b16 v[58:59], v202 offset:31744
	ds_read_b64_tr_b16 v[60:61], v202 offset:32256
	v_mfma_f32_32x32x16_bf16 v[82:97], v[162:165], v[138:141], v[82:97]
	v_add_f32_e32 v78, v64, v78
	v_add_f32_e32 v78, v65, v78
	v_add_f32_e32 v78, 0, v78
	v_cvt_pk_bf16_f32 v132, v62, v63
	v_cvt_pk_bf16_f32 v133, v64, v65
	v_lshl_add_u64 v[62:63], v[210:211], 0, s[80:81]
	s_add_i32 s14, s19, s25
	s_mov_b32 s15, m0
	s_mov_b32 m0, s14
	s_nop 0
	global_load_lds_dwordx4 v[62:63], off
	s_mov_b32 m0, s15
	v_lshl_add_u64 v[62:63], v[208:209], 0, s[80:81]
	s_add_i32 s14, s18, s26
	s_mov_b32 s15, m0
	s_mov_b32 m0, s14
	s_nop 0
	global_load_lds_dwordx4 v[62:63], off
	s_mov_b32 m0, s15
	v_max_f32_e32 v62, v98, v99
	v_max3_f32 v63, v100, v101, v83
	v_max3_f32 v62, v62, v82, v84
	v_max3_f32 v62, v62, v85, v102
	v_max3_f32 v63, v63, v104, v105
	v_max3_f32 v62, v62, v103, v86
	v_max3_f32 v63, v63, v88, v89
	v_max3_f32 v62, v62, v87, v106
	v_max3_f32 v63, v63, v108, v109
	v_max3_f32 v62, v62, v107, v90
	v_max3_f32 v63, v63, v92, v93
	v_max3_f32 v62, v62, v91, v110
	v_max3_f32 v63, v63, v112, v113
	v_max3_f32 v62, v62, v111, v94
	v_max3_f32 v63, v63, v96, v97
	v_max3_f32 v62, v62, v95, v63
	v_mov_b32_e32 v63, v62
	s_nop 1
	v_permlane32_swap_b32_e32 v62, v63
	v_max_f32_e32 v62, v62, v63
	v_cmp_lt_f32_e32 vcc, s78, v62
	s_cmp_lg_u64 vcc, 0
	v_add_f32_e32 v238, v238, v78
	s_cselect_b64 s[14:15], -1, 0
	s_cbranch_vccnz .LBB0_717

.LBB0_712:
	s_add_i32 s14, s18, 0x2000
	s_cmpk_lg_i32 s18, 0x4000
	s_cselect_b32 s27, s14, 0
	v_add_u32_e32 v202, s19, v237
	ds_read_b64_tr_b16 v[166:167], v202 offset:24576
	ds_read_b64_tr_b16 v[168:169], v202 offset:25088
	s_waitcnt lgkmcnt(9)
	v_mfma_f32_32x32x16_bf16 v[66:81], v[62:65], v[158:161], v[34:49]
	v_add_f32_e32 v50, v98, v99
	v_add_f32_e32 v50, v100, v50
	v_add_f32_e32 v50, v101, v50
	v_add_f32_e32 v50, v102, v50
	v_add_f32_e32 v50, v103, v50
	v_cvt_pk_bf16_f32 v150, v98, v99
	v_cvt_pk_bf16_f32 v151, v100, v101
	ds_read_b64_tr_b16 v[162:163], v202 offset:28672
	ds_read_b64_tr_b16 v[164:165], v202 offset:29184
	v_add_f32_e32 v50, v104, v50
	v_add_f32_e32 v50, v105, v50
	v_add_f32_e32 v50, v106, v50
	v_add_f32_e32 v130, v107, v50
	s_waitcnt lgkmcnt(10)
	v_mfma_f32_32x32x16_bf16 v[50:65], v[190:193], v[158:161], v[34:49]
	v_cvt_pk_bf16_f32 v152, v102, v103
	v_cvt_pk_bf16_f32 v153, v104, v105
	ds_read_b64_tr_b16 v[98:99], v202 offset:25600
	ds_read_b64_tr_b16 v[100:101], v202 offset:26112
	s_waitcnt lgkmcnt(11)
	v_mfma_f32_32x32x16_bf16 v[66:81], v[194:197], v[154:157], v[66:81]
	v_add_f32_e32 v102, v108, v130
	v_add_f32_e32 v102, v109, v102
	v_add_f32_e32 v102, v110, v102
	v_add_f32_e32 v130, v111, v102
	v_cvt_pk_bf16_f32 v142, v106, v107
	v_cvt_pk_bf16_f32 v143, v108, v109
	ds_read_b64_tr_b16 v[102:103], v202 offset:29696
	ds_read_b64_tr_b16 v[104:105], v202 offset:30208
	s_waitcnt lgkmcnt(12)
	v_mfma_f32_32x32x16_bf16 v[50:65], v[186:189], v[154:157], v[50:65]
	v_add_f32_e32 v106, v112, v130
	v_add_f32_e32 v106, v113, v106
	v_add_f32_e32 v106, v82, v106
	v_add_f32_e32 v130, v83, v106
	v_cvt_pk_bf16_f32 v144, v110, v111
	v_cvt_pk_bf16_f32 v145, v112, v113
	ds_read_b64_tr_b16 v[106:107], v202 offset:26624
	ds_read_b64_tr_b16 v[108:109], v202 offset:27136
	s_waitcnt lgkmcnt(13)
	v_mfma_f32_32x32x16_bf16 v[66:81], v[182:185], v[146:149], v[66:81]
	v_add_f32_e32 v110, v84, v130
	v_add_f32_e32 v110, v85, v110
	v_add_f32_e32 v110, v86, v110
	v_add_f32_e32 v110, v87, v110
	v_cvt_pk_bf16_f32 v134, v82, v83
	v_cvt_pk_bf16_f32 v135, v84, v85
	ds_read_b64_tr_b16 v[82:83], v202 offset:30720
	ds_read_b64_tr_b16 v[84:85], v202 offset:31232
	s_waitcnt lgkmcnt(14)
	v_mfma_f32_32x32x16_bf16 v[50:65], v[178:181], v[146:149], v[50:65]
	v_add_f32_e32 v110, v88, v110
	v_add_f32_e32 v110, v89, v110
	v_add_f32_e32 v110, v90, v110
	v_add_f32_e32 v110, v91, v110
	v_cvt_pk_bf16_f32 v136, v86, v87
	v_cvt_pk_bf16_f32 v137, v88, v89
	ds_read_b64_tr_b16 v[86:87], v202 offset:27648
	ds_read_b64_tr_b16 v[88:89], v202 offset:28160
	s_waitcnt lgkmcnt(14)
	v_mfma_f32_32x32x16_bf16 v[66:81], v[174:177], v[138:141], v[66:81]
	v_add_f32_e32 v110, v92, v110
	v_add_f32_e32 v110, v93, v110
	v_add_f32_e32 v110, v94, v110
	v_add_f32_e32 v110, v95, v110
	v_cvt_pk_bf16_f32 v130, v90, v91
	v_cvt_pk_bf16_f32 v131, v92, v93
	ds_read_b64_tr_b16 v[90:91], v202 offset:31744
	ds_read_b64_tr_b16 v[92:93], v202 offset:32256
	v_mfma_f32_32x32x16_bf16 v[50:65], v[170:173], v[138:141], v[50:65]
	v_add_f32_e32 v110, v96, v110
	v_add_f32_e32 v110, v97, v110
	v_add_f32_e32 v110, 0, v110
	v_cvt_pk_bf16_f32 v132, v94, v95
	v_cvt_pk_bf16_f32 v133, v96, v97
	v_max_f32_e32 v94, v66, v67
	s_nop 3
	v_max3_f32 v95, v68, v69, v51
	v_max3_f32 v94, v94, v50, v52
	v_max3_f32 v94, v94, v53, v70
	v_max3_f32 v95, v95, v72, v73
	v_max3_f32 v94, v94, v71, v54
	v_max3_f32 v95, v95, v56, v57
	v_max3_f32 v94, v94, v55, v74
	v_max3_f32 v95, v95, v76, v77
	v_max3_f32 v94, v94, v75, v58
	v_max3_f32 v95, v95, v60, v61
	v_max3_f32 v94, v94, v59, v78
	v_max3_f32 v95, v95, v80, v81
	v_max3_f32 v94, v94, v79, v62
	v_max3_f32 v95, v95, v64, v65
	v_max3_f32 v94, v94, v63, v95
	v_mov_b32_e32 v95, v94
	s_nop 1
	v_permlane32_swap_b32_e32 v94, v95
	s_add_i32 s14, s18, s25
	s_mov_b32 s15, m0
	s_mov_b32 m0, s14
	s_nop 0
	global_load_lds_dwordx4 v[210:211], off
	s_mov_b32 m0, s15
	v_max_f32_e32 v94, v94, v95
	s_add_i32 s14, s27, s26
	s_mov_b32 s15, m0
	s_mov_b32 m0, s14
	s_nop 0
	global_load_lds_dwordx4 v[208:209], off
	s_mov_b32 m0, s15
	v_cmp_lt_f32_e32 vcc, s78, v94
	s_cmp_lg_u64 vcc, 0
	v_add_f32_e32 v238, v238, v110
	s_cselect_b64 s[14:15], -1, 0
	s_cbranch_vccnz .LBB0_720
